# cooperative row sum-of-squares (8 loads/lane + ds_bpermute) extended to MLA_IN, DIFF_IN, GQA_IN epilogues
# baseline (speedup 1.0000x reference)
.LBB0_266:
	v_add_u32_e32 v164, s76, v173
	v_and_b32_e32 v222, 31, v199
	v_bfe_u32 v223, v199, 5, 1
	v_lshlrev_b32_e32 v224, 2, v223
	v_sub_u32_e32 v222, v222, v224
	v_add_lshl_u32 v222, v222, v164, 2
	v_lshlrev_b32_e32 v223, 4, v223
	global_load_dword v194, v222, s[18:19]
	v_add_u32_e32 v224, 0x10000, v222
	global_load_dword v195, v224, s[18:19]
	v_add_u32_e32 v224, 0x20000, v222
	global_load_dword v196, v224, s[18:19]
	v_add_u32_e32 v224, 0x30000, v222
	global_load_dword v197, v224, s[18:19]
	v_add_u32_e32 v224, 0x40000, v222
	global_load_dword v202, v224, s[18:19]
	v_add_u32_e32 v224, 0x50000, v222
	global_load_dword v203, v224, s[18:19]
	v_add_u32_e32 v224, 0x60000, v222
	global_load_dword v204, v224, s[18:19]
	v_add_u32_e32 v224, 0x70000, v222
	global_load_dword v205, v224, s[18:19]
	s_waitcnt vmcnt(0)
	v_add_f32_e32 v194, v194, v195
	v_add_f32_e32 v196, v196, v197
	v_add_f32_e32 v202, v202, v203
	v_add_f32_e32 v204, v204, v205
	v_add_f32_e32 v194, v194, v196
	v_add_f32_e32 v202, v202, v204
	v_add_f32_e32 v194, v194, v202
	v_fmamk_f32 v194, v194, 0x3a800000, v209
	v_rsq_f32_e32 v194, v194
	s_nop 1
	ds_bpermute_b32 v225, v223, v194
	ds_bpermute_b32 v230, v223, v194 offset:4
	ds_bpermute_b32 v231, v223, v194 offset:8
	ds_bpermute_b32 v232, v223, v194 offset:12
	ds_bpermute_b32 v233, v223, v194 offset:32
	ds_bpermute_b32 v234, v223, v194 offset:36
	ds_bpermute_b32 v235, v223, v194 offset:40
	ds_bpermute_b32 v236, v223, v194 offset:44
	ds_bpermute_b32 v237, v223, v194 offset:64
	ds_bpermute_b32 v238, v223, v194 offset:68
	ds_bpermute_b32 v239, v223, v194 offset:72
	ds_bpermute_b32 v240, v223, v194 offset:76
	ds_bpermute_b32 v241, v223, v194 offset:96
	ds_bpermute_b32 v242, v223, v194 offset:100
	ds_bpermute_b32 v243, v223, v194 offset:104
	ds_bpermute_b32 v244, v223, v194 offset:108
	s_waitcnt lgkmcnt(0)
	s_lshl_b64 s[80:81], s[80:81], 2
	s_add_u32 s80, s84, s80
	s_addc_u32 s81, s85, s81
	s_cmp_gt_i32 s95, 23
	v_or_b32_e32 v92, 16, v164
	v_ashrrev_i32_e32 v93, 31, v92
	v_lshl_add_u64 v[92:93], v[92:93], 2, s[18:19]
	v_or_b32_e32 v68, 24, v164
	v_add_co_u32_e32 v94, vcc, s91, v92
	v_ashrrev_i32_e32 v69, 31, v68
	s_nop 0
	v_addc_co_u32_e32 v95, vcc, 0, v93, vcc
	v_lshl_add_u64 v[80:81], v[68:69], 2, s[18:19]
	v_add_co_u32_e32 v88, vcc, s90, v80
	s_nop 1
	v_addc_co_u32_e32 v89, vcc, 0, v81, vcc
	v_add_co_u32_e32 v84, vcc, s91, v80
	s_nop 1
	v_addc_co_u32_e32 v85, vcc, 0, v81, vcc
	v_add_co_u32_e32 v80, vcc, s92, v80
	s_nop 1
	v_addc_co_u32_e32 v81, vcc, 0, v81, vcc
	v_or_b32_e32 v76, s78, v156
	v_ashrrev_i32_e32 v77, 31, v76
	v_lshl_add_u64 v[64:65], v[76:77], 2, s[80:81]
	global_load_dword v81, v[64:65], off
	global_load_dword v80, v[64:65], off offset:128
	global_load_dword v82, v[64:65], off offset:256
	global_load_dword v83, v[64:65], off offset:384
	v_mov_b32_e32 v65, v48
	v_mov_b32_e32 v48, v33
	v_mov_b32_e32 v33, v50
	v_mov_b32_e32 v50, v35
	s_mov_b64 s[80:81], -1
	v_mov_b32_e32 v94, v234
	v_mov_b32_e32 v96, v235
	v_mov_b32_e32 v98, v236
	v_mov_b32_e32 v100, v237
	v_mov_b32_e32 v84, v225
	v_mov_b32_e32 v102, v238
	v_mov_b32_e32 v86, v230
	v_mov_b32_e32 v104, v239
	v_mov_b32_e32 v88, v231
	v_mov_b32_e32 v106, v240
	v_mov_b32_e32 v90, v232
	v_mov_b32_e32 v108, v241
	v_mov_b32_e32 v92, v233
	v_mov_b32_e32 v110, v242
	v_mov_b32_e32 v112, v243
	v_mov_b32_e32 v114, v244
	v_mov_b32_e32 v64, v32
	v_mov_b32_e32 v32, v34
	s_waitcnt vmcnt(2)
	v_pk_fma_f32 v[72:73], v[32:33], v[88:89], v[80:81] op_sel_hi:[1,0,1]
	v_mov_b32_e32 v32, v36
	v_mov_b32_e32 v33, v52
	v_pk_fma_f32 v[68:69], v[32:33], v[92:93], v[80:81] op_sel_hi:[1,0,1]
	v_mov_b32_e32 v32, v38
	v_mov_b32_e32 v33, v54
	v_pk_fma_f32 v[78:79], v[64:65], v[84:85], v[80:81] op_sel_hi:[1,0,1]
	v_mov_b32_e32 v52, v37
	v_pk_fma_f32 v[64:65], v[32:33], v[96:97], v[80:81] op_sel_hi:[1,0,1]
	v_mov_b32_e32 v32, v40
	v_mov_b32_e32 v33, v56
	v_pk_fma_f32 v[66:67], v[52:53], v[94:95], v[80:81] op_sel_hi:[1,0,1]
	v_pk_fma_f32 v[52:53], v[32:33], v[100:101], v[80:81] op_sel_hi:[1,0,1]
	v_mov_b32_e32 v32, v42
	v_mov_b32_e32 v33, v58
	v_pk_fma_f32 v[74:75], v[48:49], v[86:87], v[80:81] op_sel_hi:[1,0,1]
	v_pk_fma_f32 v[48:49], v[32:33], v[104:105], v[80:81] op_sel_hi:[1,0,1]
	v_mov_b32_e32 v32, v44
	v_mov_b32_e32 v33, v60
	v_mov_b32_e32 v54, v39
	v_mov_b32_e32 v56, v41
	v_mov_b32_e32 v58, v43
	v_pk_fma_f32 v[38:39], v[32:33], v[108:109], v[80:81] op_sel_hi:[1,0,1]
	v_mov_b32_e32 v60, v45
	v_mov_b32_e32 v32, v46
	v_mov_b32_e32 v33, v62
	v_mov_b32_e32 v62, v47
	v_pk_fma_f32 v[70:71], v[50:51], v[90:91], v[80:81] op_sel_hi:[1,0,1]
	v_pk_fma_f32 v[54:55], v[54:55], v[98:99], v[80:81] op_sel_hi:[1,0,1]
	v_pk_fma_f32 v[50:51], v[56:57], v[102:103], v[80:81] op_sel_hi:[1,0,1]
	v_pk_fma_f32 v[40:41], v[58:59], v[106:107], v[80:81] op_sel_hi:[1,0,1]
	v_pk_fma_f32 v[36:37], v[60:61], v[110:111], v[80:81] op_sel_hi:[1,0,1]
	v_pk_fma_f32 v[34:35], v[32:33], v[112:113], v[80:81] op_sel_hi:[1,0,1]
	v_pk_fma_f32 v[32:33], v[62:63], v[114:115], v[80:81] op_sel_hi:[1,0,1]
	s_waitcnt vmcnt(1)
	v_fma_f32 v57, v16, v84, v82
	v_fma_f32 v47, v17, v86, v82
	v_fma_f32 v46, v18, v88, v82
	v_fma_f32 v45, v19, v90, v82
	v_fma_f32 v44, v20, v92, v82
	v_fma_f32 v43, v21, v94, v82
	v_fma_f32 v42, v22, v96, v82
	v_fma_f32 v23, v23, v98, v82
	v_fma_f32 v22, v24, v100, v82
	v_fma_f32 v21, v25, v102, v82
	v_fma_f32 v20, v26, v104, v82
	v_fma_f32 v19, v27, v106, v82
	v_fma_f32 v18, v28, v108, v82
	v_fma_f32 v17, v29, v110, v82
	v_fma_f32 v16, v30, v112, v82
	v_fmac_f32_e32 v82, v31, v114
	s_waitcnt vmcnt(0)
	v_fma_f32 v56, v0, v84, v83
	v_fma_f32 v31, v1, v86, v83
	v_fma_f32 v30, v2, v88, v83
	v_fma_f32 v29, v3, v90, v83
	v_fma_f32 v28, v4, v92, v83
	v_fma_f32 v27, v5, v94, v83
	v_fma_f32 v26, v6, v96, v83
	v_fma_f32 v25, v7, v98, v83
	v_fma_f32 v24, v8, v100, v83
	v_fma_f32 v9, v9, v102, v83
	v_fma_f32 v8, v10, v104, v83
	v_fma_f32 v7, v11, v106, v83
	v_fma_f32 v6, v12, v108, v83
	v_fma_f32 v5, v13, v110, v83
	v_fma_f32 v4, v14, v112, v83
	v_fmac_f32_e32 v83, v15, v114
	s_cbranch_scc0 .LBB0_496
	v_cndmask_b32_e64 v0, 0, 1, s[4:5]
	s_cmp_gt_u32 s10, 4
	v_cmp_ne_u32_e64 s[4:5], 1, v0
	s_cbranch_scc0 .LBB0_333
	v_mov_b32_e32 v0, s93
	ds_read_b64 v[0:1], v0
	v_and_b32_e32 v11, 64, v214
	v_xor_b32_e32 v10, 1, v214
	v_add_u32_e32 v13, 64, v11
	v_pk_mul_f32 v[2:3], v[78:79], v[78:79]
	s_waitcnt lgkmcnt(0)
	v_readfirstlane_b32 s80, v0
	v_readfirstlane_b32 s81, v1
	s_nop 4
	global_load_dword v1, v210, s[80:81] offset:1280
	global_load_dword v0, v210, s[80:81] offset:1408
	v_cmp_lt_i32_e32 vcc, v10, v13
	v_add_f32_e32 v2, v3, v2
	v_xor_b32_e32 v11, 4, v214
	v_cndmask_b32_e32 v3, v214, v10, vcc
	v_lshlrev_b32_e32 v14, 2, v3
	ds_bpermute_b32 v3, v14, v2
	v_xor_b32_e32 v10, 2, v214
	v_cmp_lt_i32_e32 vcc, v10, v13
	v_xor_b32_e32 v12, 8, v214
	v_xor_b32_e32 v15, 16, v214
	v_cndmask_b32_e32 v10, v214, v10, vcc
	v_lshlrev_b32_e32 v10, 2, v10
	s_waitcnt lgkmcnt(0)
	v_add_f32_e32 v2, v2, v3
	ds_bpermute_b32 v3, v10, v2
	v_cmp_lt_i32_e32 vcc, v11, v13
	s_mov_b64 s[80:81], -1
	s_waitcnt lgkmcnt(0)
	v_add_f32_e32 v2, v2, v3
	v_cndmask_b32_e32 v11, v214, v11, vcc
	v_lshlrev_b32_e32 v11, 2, v11
	ds_bpermute_b32 v3, v11, v2
	v_cmp_lt_i32_e32 vcc, v12, v13
	s_waitcnt lgkmcnt(0)
	v_add_f32_e32 v2, v2, v3
	v_cndmask_b32_e32 v12, v214, v12, vcc
	v_lshlrev_b32_e32 v12, 2, v12
	ds_bpermute_b32 v3, v12, v2
	v_cmp_lt_i32_e32 vcc, v15, v13
	s_waitcnt lgkmcnt(0)
	v_add_f32_e32 v2, v2, v3
	v_cndmask_b32_e32 v13, v214, v15, vcc
	v_lshlrev_b32_e32 v13, 2, v13
	ds_bpermute_b32 v3, v13, v2
	s_and_b64 vcc, exec, s[4:5]
	s_waitcnt lgkmcnt(0)
	v_add_f32_e32 v2, v2, v3
	v_fmamk_f32 v2, v2, 0x3c800000, v209
	v_rsq_f32_e32 v2, v2
	s_waitcnt vmcnt(0)
	v_pk_mul_f32 v[2:3], v[0:1], v[2:3] op_sel_hi:[1,0]
	s_nop 0
	v_pk_mul_f32 v[2:3], v[78:79], v[2:3]
	s_cbranch_vccnz .LBB0_270
	v_lshl_or_b32 v58, v164, 6, v156
	v_ashrrev_i32_e32 v59, 31, v58
	v_lshl_add_u64 v[58:59], v[58:59], 2, s[24:25]
	s_mov_b64 s[80:81], 0
	global_store_dword v[58:59], v3, off sc1
	global_store_dword v[58:59], v2, off offset:128 sc1

.LBB0_836:
	v_add_u32_e32 v148, s68, v160
	v_and_b32_e32 v226, 31, v199
	v_bfe_u32 v227, v199, 5, 1
	v_lshlrev_b32_e32 v229, 2, v227
	v_sub_u32_e32 v226, v226, v229
	v_add_lshl_u32 v226, v226, v148, 2
	v_lshlrev_b32_e32 v227, 4, v227
	global_load_dword v144, v226, s[18:19]
	v_add_u32_e32 v229, 0x10000, v226
	global_load_dword v145, v229, s[18:19]
	v_add_u32_e32 v229, 0x20000, v226
	global_load_dword v146, v229, s[18:19]
	v_add_u32_e32 v229, 0x30000, v226
	global_load_dword v147, v229, s[18:19]
	v_add_u32_e32 v229, 0x40000, v226
	global_load_dword v184, v229, s[18:19]
	v_add_u32_e32 v229, 0x50000, v226
	global_load_dword v185, v229, s[18:19]
	v_add_u32_e32 v229, 0x60000, v226
	global_load_dword v186, v229, s[18:19]
	v_add_u32_e32 v229, 0x70000, v226
	global_load_dword v187, v229, s[18:19]
	s_waitcnt vmcnt(0)
	v_add_f32_e32 v144, v144, v145
	v_add_f32_e32 v146, v146, v147
	v_add_f32_e32 v184, v184, v185
	v_add_f32_e32 v186, v186, v187
	v_add_f32_e32 v144, v144, v146
	v_add_f32_e32 v184, v184, v186
	v_add_f32_e32 v144, v144, v184
	v_fmamk_f32 v144, v144, 0x3a800000, v196
	v_rsq_f32_e32 v144, v144
	s_nop 1
	ds_bpermute_b32 v230, v227, v144
	ds_bpermute_b32 v231, v227, v144 offset:4
	ds_bpermute_b32 v232, v227, v144 offset:8
	ds_bpermute_b32 v233, v227, v144 offset:12
	ds_bpermute_b32 v234, v227, v144 offset:32
	ds_bpermute_b32 v235, v227, v144 offset:36
	ds_bpermute_b32 v236, v227, v144 offset:40
	ds_bpermute_b32 v237, v227, v144 offset:44
	ds_bpermute_b32 v238, v227, v144 offset:64
	ds_bpermute_b32 v239, v227, v144 offset:68
	ds_bpermute_b32 v240, v227, v144 offset:72
	ds_bpermute_b32 v241, v227, v144 offset:76
	ds_bpermute_b32 v242, v227, v144 offset:96
	ds_bpermute_b32 v243, v227, v144 offset:100
	ds_bpermute_b32 v244, v227, v144 offset:104
	ds_bpermute_b32 v245, v227, v144 offset:108
	s_waitcnt lgkmcnt(0)
	v_or_b32_e32 v150, 8, v148
	v_or_b32_e32 v152, 9, v148
	v_or_b32_e32 v154, 16, v148
	v_ashrrev_i32_e32 v155, 31, v154
	s_lshl_b64 s[72:73], s[72:73], 2
	s_add_u32 s72, s10, s72
	s_addc_u32 s73, s11, s73
	s_ashr_i32 s8, s86, 3
	v_lshl_add_u64 v[92:93], v[154:155], 2, s[18:19]
	v_or_b32_e32 v84, 24, v148
	v_ashrrev_i32_e32 v85, 31, v84
	v_add_co_u32_e32 v94, vcc, s82, v92
	s_nop 1
	v_addc_co_u32_e32 v95, vcc, 0, v93, vcc
	v_or_b32_e32 v80, 17, v148
	v_ashrrev_i32_e32 v81, 31, v80
	v_lshl_add_u64 v[92:93], v[80:81], 2, s[18:19]
	v_or_b32_e32 v88, 25, v148
	v_ashrrev_i32_e32 v89, 31, v88
	v_or_b32_e32 v66, s0, v140
	v_ashrrev_i32_e32 v67, 31, v66
	v_lshl_add_u64 v[66:67], v[66:67], 2, s[72:73]
	global_load_dword v91, v[66:67], off
	global_load_dword v90, v[66:67], off offset:128
	global_load_dword v105, v[66:67], off offset:256
	global_load_dword v104, v[66:67], off offset:384
	s_and_b32 s72, s86, 7
	s_cmp_gt_i32 s8, 1
	v_mov_b32_e32 v92, v230
	v_mov_b32_e32 v94, v231
	v_mov_b32_e32 v96, v232
	v_mov_b32_e32 v98, v233
	v_mov_b32_e32 v100, v234
	v_mov_b32_e32 v102, v235
	v_mov_b32_e32 v106, v236
	v_mov_b32_e32 v108, v237
	v_mov_b32_e32 v110, v238
	v_mov_b32_e32 v112, v239
	v_mov_b32_e32 v114, v240
	v_mov_b32_e32 v116, v241
	v_mov_b32_e32 v118, v242
	v_mov_b32_e32 v120, v243
	v_mov_b32_e32 v122, v244
	v_mov_b32_e32 v124, v245
	v_mov_b32_e32 v64, v32
	v_mov_b32_e32 v65, v48
	v_mov_b32_e32 v48, v33
	v_mov_b32_e32 v32, v34
	v_mov_b32_e32 v33, v50
	s_waitcnt vmcnt(2)
	v_pk_fma_f32 v[78:79], v[32:33], v[96:97], v[90:91] op_sel_hi:[1,0,1]
	v_mov_b32_e32 v32, v36
	v_mov_b32_e32 v33, v52
	v_pk_fma_f32 v[70:71], v[32:33], v[100:101], v[90:91] op_sel_hi:[1,0,1]
	v_mov_b32_e32 v32, v38
	v_mov_b32_e32 v33, v54
	v_pk_fma_f32 v[76:77], v[32:33], v[106:107], v[90:91] op_sel_hi:[1,0,1]
	v_mov_b32_e32 v32, v40
	v_mov_b32_e32 v33, v56
	v_pk_fma_f32 v[66:67], v[32:33], v[110:111], v[90:91] op_sel_hi:[1,0,1]
	v_mov_b32_e32 v56, v41
	v_mov_b32_e32 v32, v42
	v_mov_b32_e32 v33, v58
	v_pk_fma_f32 v[86:87], v[64:65], v[92:93], v[90:91] op_sel_hi:[1,0,1]
	v_mov_b32_e32 v52, v37
	v_pk_fma_f32 v[64:65], v[56:57], v[112:113], v[90:91] op_sel_hi:[1,0,1]
	v_pk_fma_f32 v[56:57], v[32:33], v[114:115], v[90:91] op_sel_hi:[1,0,1]
	v_mov_b32_e32 v32, v44
	v_mov_b32_e32 v33, v60
	v_pk_fma_f32 v[72:73], v[52:53], v[102:103], v[90:91] op_sel_hi:[1,0,1]
	v_pk_fma_f32 v[52:53], v[32:33], v[118:119], v[90:91] op_sel_hi:[1,0,1]
	v_mov_b32_e32 v32, v46
	v_mov_b32_e32 v33, v62
	v_pk_fma_f32 v[82:83], v[48:49], v[94:95], v[90:91] op_sel_hi:[1,0,1]
	v_pk_fma_f32 v[48:49], v[32:33], v[122:123], v[90:91] op_sel_hi:[1,0,1]
	v_mov_b32_e32 v32, v0
	v_mov_b32_e32 v33, v16
	v_mov_b32_e32 v16, v1
	v_mov_b32_e32 v0, v2
	v_mov_b32_e32 v1, v18
	s_waitcnt vmcnt(0)
	v_pk_fma_f32 v[40:41], v[0:1], v[96:97], v[104:105] op_sel_hi:[1,0,1]
	v_mov_b32_e32 v0, v4
	v_mov_b32_e32 v1, v20
	v_pk_fma_f32 v[36:37], v[0:1], v[100:101], v[104:105] op_sel_hi:[1,0,1]
	v_mov_b32_e32 v0, v6
	v_mov_b32_e32 v1, v22
	v_mov_b32_e32 v60, v45
	v_pk_fma_f32 v[44:45], v[32:33], v[92:93], v[104:105] op_sel_hi:[1,0,1]
	v_mov_b32_e32 v20, v5
	v_pk_fma_f32 v[32:33], v[0:1], v[106:107], v[104:105] op_sel_hi:[1,0,1]
	v_mov_b32_e32 v0, v8
	v_mov_b32_e32 v1, v24
	v_mov_b32_e32 v50, v35
	v_pk_fma_f32 v[34:35], v[20:21], v[102:103], v[104:105] op_sel_hi:[1,0,1]
	v_pk_fma_f32 v[20:21], v[0:1], v[110:111], v[104:105] op_sel_hi:[1,0,1]
	v_mov_b32_e32 v0, v10
	v_mov_b32_e32 v1, v26
	v_mov_b32_e32 v58, v43
	v_pk_fma_f32 v[42:43], v[16:17], v[94:95], v[104:105] op_sel_hi:[1,0,1]
	v_pk_fma_f32 v[16:17], v[0:1], v[114:115], v[104:105] op_sel_hi:[1,0,1]
	v_mov_b32_e32 v0, v12
	v_mov_b32_e32 v1, v28
	v_mov_b32_e32 v54, v39
	v_mov_b32_e32 v62, v47
	v_mov_b32_e32 v18, v3
	v_mov_b32_e32 v22, v7
	v_mov_b32_e32 v24, v9
	v_mov_b32_e32 v26, v11
	v_pk_fma_f32 v[6:7], v[0:1], v[118:119], v[104:105] op_sel_hi:[1,0,1]
	v_mov_b32_e32 v28, v13
	v_mov_b32_e32 v0, v14
	v_mov_b32_e32 v1, v30
	v_mov_b32_e32 v30, v15
	v_pk_fma_f32 v[74:75], v[50:51], v[98:99], v[90:91] op_sel_hi:[1,0,1]
	v_pk_fma_f32 v[68:69], v[54:55], v[108:109], v[90:91] op_sel_hi:[1,0,1]
	v_pk_fma_f32 v[54:55], v[58:59], v[116:117], v[90:91] op_sel_hi:[1,0,1]
	v_pk_fma_f32 v[50:51], v[60:61], v[120:121], v[90:91] op_sel_hi:[1,0,1]
	v_pk_fma_f32 v[46:47], v[62:63], v[124:125], v[90:91] op_sel_hi:[1,0,1]
	v_pk_fma_f32 v[38:39], v[18:19], v[98:99], v[104:105] op_sel_hi:[1,0,1]
	v_pk_fma_f32 v[22:23], v[22:23], v[108:109], v[104:105] op_sel_hi:[1,0,1]
	v_pk_fma_f32 v[18:19], v[24:25], v[112:113], v[104:105] op_sel_hi:[1,0,1]
	v_pk_fma_f32 v[8:9], v[26:27], v[116:117], v[104:105] op_sel_hi:[1,0,1]
	v_pk_fma_f32 v[4:5], v[28:29], v[120:121], v[104:105] op_sel_hi:[1,0,1]
	v_pk_fma_f32 v[2:3], v[0:1], v[122:123], v[104:105] op_sel_hi:[1,0,1]
	v_pk_fma_f32 v[0:1], v[30:31], v[124:125], v[104:105] op_sel_hi:[1,0,1]
	s_mov_b64 s[0:1], -1
	s_cbranch_scc0 .LBB0_846
	s_and_b64 s[0:1], s[4:5], exec
	s_cselect_b32 s0, 0x100, 0
	s_add_i32 s0, s69, s0
	v_add_u32_e32 v27, s0, v160
	s_lshl_b32 s0, s87, 18
	s_lshl_b32 s1, s72, 15
	s_or_b32 s75, s0, s1
	s_lshl_b32 s0, s87, 10
	s_lshl_b32 s73, s72, 7
	s_or_b32 s87, s0, s73
	v_or_b32_e32 v29, s87, v140
	v_mul_lo_u32 v29, v29, s76
	v_or_b32_e32 v28, s75, v161
	v_add_u32_e32 v29, 0x800000, v29
	v_cndmask_b32_e64 v60, v28, v29, s[4:5]
	v_add_u32_e32 v28, v60, v27
	v_ashrrev_i32_e32 v29, 31, v28
	v_cvt_pk_bf16_f32 v30, v87, v83
	v_cvt_pk_bf16_f32 v31, v79, v75
	v_lshl_add_u64 v[28:29], v[28:29], 1, s[20:21]
	global_store_dwordx2 v[28:29], v[30:31], off sc1
	v_or_b32_e32 v28, 8, v27
	v_add_u32_e32 v30, v60, v28
	v_ashrrev_i32_e32 v31, 31, v30
	v_cvt_pk_bf16_f32 v58, v71, v73
	v_cvt_pk_bf16_f32 v59, v77, v69
	v_lshl_add_u64 v[30:31], v[30:31], 1, s[20:21]
	v_or_b32_e32 v29, 16, v27
	global_store_dwordx2 v[30:31], v[58:59], off sc1
	v_add_u32_e32 v30, v60, v29
	v_ashrrev_i32_e32 v31, 31, v30
	v_cvt_pk_bf16_f32 v58, v67, v65
	v_cvt_pk_bf16_f32 v59, v57, v55
	v_lshl_add_u64 v[30:31], v[30:31], 1, s[20:21]
	global_store_dwordx2 v[30:31], v[58:59], off sc1
	v_or_b32_e32 v30, 24, v27
	v_add_u32_e32 v58, v60, v30
	v_ashrrev_i32_e32 v59, 31, v58
	v_cndmask_b32_e64 v31, 0, 1, s[70:71]
	v_or_b32_e32 v26, 1, v148
	v_or_b32_e32 v25, 2, v148
	v_or_b32_e32 v24, 3, v148
	v_or_b32_e32 v15, 10, v148
	v_or_b32_e32 v14, 11, v148
	v_or_b32_e32 v13, 18, v148
	v_or_b32_e32 v12, 19, v148
	v_or_b32_e32 v11, 26, v148
	v_or_b32_e32 v10, 27, v148
	v_cvt_pk_bf16_f32 v60, v53, v51
	v_cvt_pk_bf16_f32 v61, v49, v47
	v_lshl_add_u64 v[58:59], v[58:59], 1, s[20:21]
	v_cmp_ne_u32_e64 s[0:1], 1, v31
	s_andn2_b64 vcc, exec, s[70:71]
	global_store_dwordx2 v[58:59], v[60:61], off sc1
	s_cbranch_vccnz .LBB0_839
	v_or_b32_e32 v31, s73, v140
	v_lshl_or_b32 v58, v148, 10, v31
	v_ashrrev_i32_e32 v59, 31, v58
	v_lshl_add_u64 v[58:59], v[58:59], 2, s[22:23]
	global_store_dword v[58:59], v87, off sc1
	v_lshl_or_b32 v58, v26, 10, v31
	v_ashrrev_i32_e32 v59, 31, v58
	v_lshl_add_u64 v[58:59], v[58:59], 2, s[22:23]
	global_store_dword v[58:59], v83, off sc1
	v_lshl_or_b32 v58, v25, 10, v31
	v_ashrrev_i32_e32 v59, 31, v58
	v_lshl_add_u64 v[58:59], v[58:59], 2, s[22:23]
	global_store_dword v[58:59], v79, off sc1
	v_lshl_or_b32 v58, v24, 10, v31
	v_ashrrev_i32_e32 v59, 31, v58
	v_lshl_add_u64 v[58:59], v[58:59], 2, s[22:23]
	global_store_dword v[58:59], v75, off sc1
	v_lshl_or_b32 v58, v150, 10, v31
	v_ashrrev_i32_e32 v59, 31, v58
	v_lshl_add_u64 v[58:59], v[58:59], 2, s[22:23]
	global_store_dword v[58:59], v71, off sc1
	v_lshl_or_b32 v58, v152, 10, v31
	v_ashrrev_i32_e32 v59, 31, v58
	v_lshl_add_u64 v[58:59], v[58:59], 2, s[22:23]
	global_store_dword v[58:59], v73, off sc1
	v_lshl_or_b32 v58, v15, 10, v31
	v_ashrrev_i32_e32 v59, 31, v58
	v_lshl_add_u64 v[58:59], v[58:59], 2, s[22:23]
	global_store_dword v[58:59], v77, off sc1
	v_lshl_or_b32 v58, v14, 10, v31
	v_ashrrev_i32_e32 v59, 31, v58
	v_lshl_add_u64 v[58:59], v[58:59], 2, s[22:23]
	global_store_dword v[58:59], v69, off sc1
	v_lshl_or_b32 v58, v154, 10, v31
	v_ashrrev_i32_e32 v59, 31, v58
	v_lshl_add_u64 v[58:59], v[58:59], 2, s[22:23]
	global_store_dword v[58:59], v67, off sc1
	v_lshl_or_b32 v58, v80, 10, v31
	v_ashrrev_i32_e32 v59, 31, v58
	v_lshl_add_u64 v[58:59], v[58:59], 2, s[22:23]
	global_store_dword v[58:59], v65, off sc1
	v_lshl_or_b32 v58, v13, 10, v31
	v_ashrrev_i32_e32 v59, 31, v58
	v_lshl_add_u64 v[58:59], v[58:59], 2, s[22:23]
	global_store_dword v[58:59], v57, off sc1
	v_lshl_or_b32 v58, v12, 10, v31
	v_ashrrev_i32_e32 v59, 31, v58
	v_lshl_add_u64 v[58:59], v[58:59], 2, s[22:23]
	global_store_dword v[58:59], v55, off sc1
	v_lshl_or_b32 v58, v84, 10, v31
	v_ashrrev_i32_e32 v59, 31, v58
	v_lshl_add_u64 v[58:59], v[58:59], 2, s[22:23]
	global_store_dword v[58:59], v53, off sc1
	v_lshl_or_b32 v58, v88, 10, v31
	v_ashrrev_i32_e32 v59, 31, v58
	v_lshl_add_u64 v[58:59], v[58:59], 2, s[22:23]
	global_store_dword v[58:59], v51, off sc1
	v_lshl_or_b32 v58, v11, 10, v31
	v_ashrrev_i32_e32 v59, 31, v58
	v_lshl_add_u64 v[58:59], v[58:59], 2, s[22:23]
	global_store_dword v[58:59], v49, off sc1
	v_lshl_or_b32 v58, v10, 10, v31
	v_ashrrev_i32_e32 v59, 31, v58
	v_lshl_add_u64 v[58:59], v[58:59], 2, s[22:23]
	global_store_dword v[58:59], v47, off sc1

.LBB0_1179:
	v_add_u32_e32 v118, s66, v133
	v_and_b32_e32 v226, 31, v199
	v_bfe_u32 v227, v199, 5, 1
	v_lshlrev_b32_e32 v229, 2, v227
	v_sub_u32_e32 v226, v226, v229
	v_add_lshl_u32 v226, v226, v118, 2
	v_lshlrev_b32_e32 v227, 4, v227
	global_load_dword v112, v226, s[18:19]
	v_add_u32_e32 v229, 0x10000, v226
	global_load_dword v113, v229, s[18:19]
	v_add_u32_e32 v229, 0x20000, v226
	global_load_dword v114, v229, s[18:19]
	v_add_u32_e32 v229, 0x30000, v226
	global_load_dword v115, v229, s[18:19]
	v_add_u32_e32 v229, 0x40000, v226
	global_load_dword v158, v229, s[18:19]
	v_add_u32_e32 v229, 0x50000, v226
	global_load_dword v159, v229, s[18:19]
	v_add_u32_e32 v229, 0x60000, v226
	global_load_dword v160, v229, s[18:19]
	v_add_u32_e32 v229, 0x70000, v226
	global_load_dword v161, v229, s[18:19]
	s_waitcnt vmcnt(0)
	v_add_f32_e32 v112, v112, v113
	v_add_f32_e32 v114, v114, v115
	v_add_f32_e32 v158, v158, v159
	v_add_f32_e32 v160, v160, v161
	v_add_f32_e32 v112, v112, v114
	v_add_f32_e32 v158, v158, v160
	v_add_f32_e32 v112, v112, v158
	v_fmamk_f32 v112, v112, 0x3a800000, v166
	v_rsq_f32_e32 v112, v112
	s_nop 1
	ds_bpermute_b32 v230, v227, v112
	ds_bpermute_b32 v231, v227, v112 offset:4
	ds_bpermute_b32 v232, v227, v112 offset:8
	ds_bpermute_b32 v233, v227, v112 offset:12
	ds_bpermute_b32 v234, v227, v112 offset:32
	ds_bpermute_b32 v235, v227, v112 offset:36
	ds_bpermute_b32 v236, v227, v112 offset:40
	ds_bpermute_b32 v237, v227, v112 offset:44
	ds_bpermute_b32 v238, v227, v112 offset:64
	ds_bpermute_b32 v239, v227, v112 offset:68
	ds_bpermute_b32 v240, v227, v112 offset:72
	ds_bpermute_b32 v241, v227, v112 offset:76
	ds_bpermute_b32 v242, v227, v112 offset:96
	ds_bpermute_b32 v243, v227, v112 offset:100
	ds_bpermute_b32 v244, v227, v112 offset:104
	ds_bpermute_b32 v245, v227, v112 offset:108
	s_waitcnt lgkmcnt(0)
	v_or_b32_e32 v120, 8, v118
	v_or_b32_e32 v122, 9, v118
	s_lshl_b64 s[70:71], s[70:71], 2
	s_add_u32 s70, s10, s70
	s_addc_u32 s71, s11, s71
	s_cmpk_gt_i32 s85, 0x4f
	v_or_b32_e32 v124, 16, v118
	v_or_b32_e32 v126, 17, v118
	v_or_b32_e32 v84, 24, v118
	v_or_b32_e32 v104, 25, v118
	v_or_b32_e32 v66, s4, v108
	v_ashrrev_i32_e32 v67, 31, v66
	v_lshl_add_u64 v[66:67], v[66:67], 2, s[70:71]
	global_load_dword v97, v[66:67], off
	global_load_dword v96, v[66:67], off offset:128
	global_load_dword v95, v[66:67], off offset:256
	global_load_dword v94, v[66:67], off offset:384
	s_mov_b64 s[4:5], -1
	v_mov_b32_e32 v68, v232
	v_mov_b32_e32 v70, v233
	v_mov_b32_e32 v64, v230
	v_mov_b32_e32 v74, v234
	v_mov_b32_e32 v98, v235
	v_mov_b32_e32 v100, v236
	v_mov_b32_e32 v102, v237
	v_mov_b32_e32 v72, v32
	v_mov_b32_e32 v73, v48
	v_mov_b32_e32 v106, v238
	v_mov_b32_e32 v172, v239
	v_mov_b32_e32 v66, v231
	v_mov_b32_e32 v174, v240
	v_mov_b32_e32 v176, v241
	v_mov_b32_e32 v178, v242
	s_waitcnt vmcnt(2)
	v_pk_fma_f32 v[90:91], v[72:73], v[64:65], v[96:97] op_sel_hi:[1,0,1]
	v_mov_b32_e32 v72, v0
	v_mov_b32_e32 v73, v16
	v_mov_b32_e32 v16, v1
	v_mov_b32_e32 v0, v34
	v_mov_b32_e32 v1, v50
	v_pk_fma_f32 v[80:81], v[0:1], v[68:69], v[96:97] op_sel_hi:[1,0,1]
	v_mov_b32_e32 v0, v2
	v_mov_b32_e32 v1, v18
	s_waitcnt vmcnt(0)
	v_pk_fma_f32 v[82:83], v[0:1], v[68:69], v[94:95] op_sel_hi:[1,0,1]
	v_mov_b32_e32 v0, v36
	v_mov_b32_e32 v1, v52
	v_pk_fma_f32 v[92:93], v[72:73], v[64:65], v[94:95] op_sel_hi:[1,0,1]
	v_pk_fma_f32 v[72:73], v[0:1], v[74:75], v[96:97] op_sel_hi:[1,0,1]
	v_mov_b32_e32 v0, v4
	v_mov_b32_e32 v1, v20
	v_pk_fma_f32 v[74:75], v[0:1], v[74:75], v[94:95] op_sel_hi:[1,0,1]
	v_mov_b32_e32 v0, v38
	v_mov_b32_e32 v1, v54
	v_mov_b32_e32 v180, v243
	v_mov_b32_e32 v184, v245
	v_mov_b32_e32 v48, v33
	v_pk_fma_f32 v[64:65], v[0:1], v[100:101], v[96:97] op_sel_hi:[1,0,1]
	v_mov_b32_e32 v0, v6
	v_mov_b32_e32 v1, v22
	v_mov_b32_e32 v182, v244
	v_pk_fma_f32 v[88:89], v[48:49], v[66:67], v[96:97] op_sel_hi:[1,0,1]
	v_pk_fma_f32 v[86:87], v[16:17], v[66:67], v[94:95] op_sel_hi:[1,0,1]
	v_pk_fma_f32 v[66:67], v[0:1], v[100:101], v[94:95] op_sel_hi:[1,0,1]
	v_mov_b32_e32 v0, v40
	v_mov_b32_e32 v1, v56
	v_mov_b32_e32 v54, v39
	v_pk_fma_f32 v[38:39], v[0:1], v[106:107], v[96:97] op_sel_hi:[1,0,1]
	v_mov_b32_e32 v0, v8
	v_mov_b32_e32 v1, v24
	v_pk_fma_f32 v[48:49], v[0:1], v[106:107], v[94:95] op_sel_hi:[1,0,1]
	v_mov_b32_e32 v24, v9
	v_mov_b32_e32 v0, v42
	v_mov_b32_e32 v1, v58
	v_mov_b32_e32 v52, v37
	v_pk_fma_f32 v[36:37], v[24:25], v[172:173], v[94:95] op_sel_hi:[1,0,1]
	v_pk_fma_f32 v[24:25], v[0:1], v[174:175], v[96:97] op_sel_hi:[1,0,1]
	v_mov_b32_e32 v0, v10
	v_mov_b32_e32 v1, v26
	v_pk_fma_f32 v[32:33], v[0:1], v[174:175], v[94:95] op_sel_hi:[1,0,1]
	v_mov_b32_e32 v0, v44
	v_mov_b32_e32 v1, v60
	v_mov_b32_e32 v18, v3
	v_pk_fma_f32 v[16:17], v[0:1], v[178:179], v[96:97] op_sel_hi:[1,0,1]
	v_mov_b32_e32 v0, v12
	v_mov_b32_e32 v1, v28
	v_pk_fma_f32 v[78:79], v[18:19], v[70:71], v[94:95] op_sel_hi:[1,0,1]
	v_pk_fma_f32 v[18:19], v[0:1], v[178:179], v[94:95] op_sel_hi:[1,0,1]
	v_mov_b32_e32 v0, v46
	v_mov_b32_e32 v1, v62
	v_mov_b32_e32 v50, v35
	v_mov_b32_e32 v20, v5
	v_mov_b32_e32 v22, v7
	v_mov_b32_e32 v56, v41
	v_mov_b32_e32 v58, v43
	v_mov_b32_e32 v26, v11
	v_mov_b32_e32 v60, v45
	v_mov_b32_e32 v28, v13
	v_pk_fma_f32 v[4:5], v[0:1], v[182:183], v[96:97] op_sel_hi:[1,0,1]
	v_mov_b32_e32 v0, v14
	v_mov_b32_e32 v1, v30
	v_mov_b32_e32 v62, v47
	v_mov_b32_e32 v30, v15
	v_pk_fma_f32 v[76:77], v[50:51], v[70:71], v[96:97] op_sel_hi:[1,0,1]
	v_pk_fma_f32 v[68:69], v[52:53], v[98:99], v[96:97] op_sel_hi:[1,0,1]
	v_pk_fma_f32 v[70:71], v[20:21], v[98:99], v[94:95] op_sel_hi:[1,0,1]
	v_pk_fma_f32 v[50:51], v[54:55], v[102:103], v[96:97] op_sel_hi:[1,0,1]
	v_pk_fma_f32 v[52:53], v[22:23], v[102:103], v[94:95] op_sel_hi:[1,0,1]
	v_pk_fma_f32 v[34:35], v[56:57], v[172:173], v[96:97] op_sel_hi:[1,0,1]
	v_pk_fma_f32 v[20:21], v[58:59], v[176:177], v[96:97] op_sel_hi:[1,0,1]
	v_pk_fma_f32 v[22:23], v[26:27], v[176:177], v[94:95] op_sel_hi:[1,0,1]
	v_pk_fma_f32 v[8:9], v[60:61], v[180:181], v[96:97] op_sel_hi:[1,0,1]
	v_pk_fma_f32 v[10:11], v[28:29], v[180:181], v[94:95] op_sel_hi:[1,0,1]
	v_pk_fma_f32 v[6:7], v[0:1], v[182:183], v[94:95] op_sel_hi:[1,0,1]
	v_pk_fma_f32 v[0:1], v[62:63], v[184:185], v[96:97] op_sel_hi:[1,0,1]
	v_pk_fma_f32 v[2:3], v[30:31], v[184:185], v[94:95] op_sel_hi:[1,0,1]
	s_cbranch_scc0 .LBB0_1189
	s_add_i32 s8, s84, -10
	s_and_b64 s[4:5], s[0:1], exec
	s_cselect_b32 s4, 0x100, 0
	s_add_i32 s4, s67, s4
	v_add_u32_e32 v31, s4, v133
	s_lshl_b32 s4, s8, 15
	s_lshl_b32 s71, s86, 8
	s_lshl_b32 s8, s8, 7
	s_add_i32 s71, s71, s8
	s_lshl_b32 s70, s86, 16
	v_or_b32_e32 v41, s71, v108
	s_add_i32 s70, s70, s4
	v_mul_lo_u32 v41, v41, s74
	v_or_b32_e32 v40, s70, v134
	v_add_u32_e32 v41, 0x200000, v41
	v_cndmask_b32_e64 v46, v40, v41, s[0:1]
	v_add_u32_e32 v40, v46, v31
	v_ashrrev_i32_e32 v41, 31, v40
	v_cvt_pk_bf16_f32 v42, v91, v89
	v_cvt_pk_bf16_f32 v43, v81, v77
	v_lshl_add_u64 v[40:41], v[40:41], 1, s[20:21]
	global_store_dwordx2 v[40:41], v[42:43], off sc1
	v_or_b32_e32 v40, 8, v31
	v_add_u32_e32 v42, v46, v40
	v_ashrrev_i32_e32 v43, 31, v42
	v_cvt_pk_bf16_f32 v44, v73, v69
	v_cvt_pk_bf16_f32 v45, v65, v51
	v_lshl_add_u64 v[42:43], v[42:43], 1, s[20:21]
	v_or_b32_e32 v41, 16, v31
	global_store_dwordx2 v[42:43], v[44:45], off sc1
	v_add_u32_e32 v42, v46, v41
	v_ashrrev_i32_e32 v43, 31, v42
	v_cvt_pk_bf16_f32 v44, v39, v35
	v_cvt_pk_bf16_f32 v45, v25, v21
	v_lshl_add_u64 v[42:43], v[42:43], 1, s[20:21]
	global_store_dwordx2 v[42:43], v[44:45], off sc1
	v_or_b32_e32 v42, 24, v31
	v_add_u32_e32 v44, v46, v42
	v_ashrrev_i32_e32 v45, 31, v44
	v_cndmask_b32_e64 v43, 0, 1, s[68:69]
	v_or_b32_e32 v30, 1, v118
	v_or_b32_e32 v29, 2, v118
	v_or_b32_e32 v28, 3, v118
	v_or_b32_e32 v27, 10, v118
	v_or_b32_e32 v26, 11, v118
	v_or_b32_e32 v15, 18, v118
	v_or_b32_e32 v14, 19, v118
	v_or_b32_e32 v13, 26, v118
	v_or_b32_e32 v12, 27, v118
	v_cvt_pk_bf16_f32 v46, v17, v9
	v_cvt_pk_bf16_f32 v47, v5, v1
	v_lshl_add_u64 v[44:45], v[44:45], 1, s[20:21]
	v_cmp_ne_u32_e64 s[4:5], 1, v43
	s_andn2_b64 vcc, exec, s[68:69]
	global_store_dwordx2 v[44:45], v[46:47], off sc1
	s_cbranch_vccnz .LBB0_1182
	v_or_b32_e32 v43, s8, v108
	v_lshl_add_u32 v44, v118, 8, v43
	v_ashrrev_i32_e32 v45, 31, v44
	v_lshl_add_u64 v[44:45], v[44:45], 2, s[22:23]
	global_store_dword v[44:45], v91, off sc1
	v_lshl_add_u32 v44, v30, 8, v43
	v_ashrrev_i32_e32 v45, 31, v44
	v_lshl_add_u64 v[44:45], v[44:45], 2, s[22:23]
	global_store_dword v[44:45], v89, off sc1
	v_lshl_add_u32 v44, v29, 8, v43
	v_ashrrev_i32_e32 v45, 31, v44
	v_lshl_add_u64 v[44:45], v[44:45], 2, s[22:23]
	global_store_dword v[44:45], v81, off sc1
	v_lshl_add_u32 v44, v28, 8, v43
	v_ashrrev_i32_e32 v45, 31, v44
	v_lshl_add_u64 v[44:45], v[44:45], 2, s[22:23]
	global_store_dword v[44:45], v77, off sc1
	v_lshl_add_u32 v44, v120, 8, v43
	v_ashrrev_i32_e32 v45, 31, v44
	v_lshl_add_u64 v[44:45], v[44:45], 2, s[22:23]
	global_store_dword v[44:45], v73, off sc1
	v_lshl_add_u32 v44, v122, 8, v43
	v_ashrrev_i32_e32 v45, 31, v44
	v_lshl_add_u64 v[44:45], v[44:45], 2, s[22:23]
	global_store_dword v[44:45], v69, off sc1
	v_lshl_add_u32 v44, v27, 8, v43
	v_ashrrev_i32_e32 v45, 31, v44
	v_lshl_add_u64 v[44:45], v[44:45], 2, s[22:23]
	global_store_dword v[44:45], v65, off sc1
	v_lshl_add_u32 v44, v26, 8, v43
	v_ashrrev_i32_e32 v45, 31, v44
	v_lshl_add_u64 v[44:45], v[44:45], 2, s[22:23]
	global_store_dword v[44:45], v51, off sc1
	v_lshl_add_u32 v44, v124, 8, v43
	v_ashrrev_i32_e32 v45, 31, v44
	v_lshl_add_u64 v[44:45], v[44:45], 2, s[22:23]
	global_store_dword v[44:45], v39, off sc1
	v_lshl_add_u32 v44, v126, 8, v43
	v_ashrrev_i32_e32 v45, 31, v44
	v_lshl_add_u64 v[44:45], v[44:45], 2, s[22:23]
	global_store_dword v[44:45], v35, off sc1
	v_lshl_add_u32 v44, v15, 8, v43
	v_ashrrev_i32_e32 v45, 31, v44
	v_lshl_add_u64 v[44:45], v[44:45], 2, s[22:23]
	global_store_dword v[44:45], v25, off sc1
	v_lshl_add_u32 v44, v14, 8, v43
	v_ashrrev_i32_e32 v45, 31, v44
	v_lshl_add_u64 v[44:45], v[44:45], 2, s[22:23]
	global_store_dword v[44:45], v21, off sc1
	v_lshl_add_u32 v44, v84, 8, v43
	v_ashrrev_i32_e32 v45, 31, v44
	v_lshl_add_u64 v[44:45], v[44:45], 2, s[22:23]
	global_store_dword v[44:45], v17, off sc1
	v_lshl_add_u32 v44, v104, 8, v43
	v_ashrrev_i32_e32 v45, 31, v44
	v_lshl_add_u64 v[44:45], v[44:45], 2, s[22:23]
	global_store_dword v[44:45], v9, off sc1
	v_lshl_add_u32 v44, v13, 8, v43
	v_ashrrev_i32_e32 v45, 31, v44
	v_lshl_add_u64 v[44:45], v[44:45], 2, s[22:23]
	global_store_dword v[44:45], v5, off sc1
	v_lshl_add_u32 v44, v12, 8, v43
	v_ashrrev_i32_e32 v45, 31, v44
	v_lshl_add_u64 v[44:45], v[44:45], 2, s[22:23]
	global_store_dword v[44:45], v1, off sc1
